# P8/P11 rms-epilogue base loads pipelined (saddr addressing, 12-16 loads in flight)
# baseline (speedup 1.0000x reference)
;     __device__ __forceinline__ void operator()(f32x4 (&acc)[2][2][4][2], const Unit& u, int wr, int wc, int fr, int fq) const {
;     ...
;             for (int m = 0; m < 4; ++m) { const size_t off = (size_t)(row0 + ai * HALF + m * 16) * ldc + col0; float s = 0.f;
; #pragma unroll
;                 for (int bj = 0; bj < 2; ++bj)
; #pragma unroll
;                     for (int n = 0; n < 2; ++n) { const f32x4 b = *(const f32x4*)(base + off + bj * HALF + n * 16); const f32x4 v = b + acc[ai][bj][m][n] * alpha; acc[ai][bj][m][n] = v; *(f32x4*)(out + off + bj * HALF + n * 16) = v;
;                         s += (v[0] * v[0] + v[1] * v[1]) + (v[2] * v[2] + v[3] * v[3]); }
;                 s += __shfl_xor(s, 16); s += __shfl_xor(s, 32);
;                 if (fq == 0) P[(ai * HALF + wr * 64 + m * 16 + fr) * 4 + wc] = s;
;                 if (m & 1) asm volatile("" ::: "memory"); }
.LBB0_563:
	s_lshl_b32 s49, s66, 8
	v_add_u32_e32 v142, s49, v148
	v_subrev_u32_e32 v188, s70, v136
	v_ashrrev_i32_e32 v143, 31, v142
	v_lshl_add_u32 v188, v142, 13, v188
	v_mov_b32_e32 v189, v188
	global_load_dwordx4 v[190:193], v189, s[70:71]
	global_load_dwordx4 v[194:197], v189, s[70:71] offset:64
	global_load_dwordx4 v[198:201], v189, s[70:71] offset:512
	global_load_dwordx4 v[202:205], v189, s[70:71] offset:576
	v_add_u32_e32 v189, 0x20000, v188
	global_load_dwordx4 v[206:209], v189, s[70:71]
	global_load_dwordx4 v[210:213], v189, s[70:71] offset:64
	global_load_dwordx4 v[214:217], v189, s[70:71] offset:512
	global_load_dwordx4 v[218:221], v189, s[70:71] offset:576
	v_add_u32_e32 v189, 0x40000, v188
	global_load_dwordx4 v[222:225], v189, s[70:71]
	global_load_dwordx4 v[226:229], v189, s[70:71] offset:64
	global_load_dwordx4 v[230:233], v189, s[70:71] offset:512
	global_load_dwordx4 v[234:237], v189, s[70:71] offset:576
	v_add_u32_e32 v189, 0x60000, v188
	global_load_dwordx4 v[238:241], v189, s[70:71]
	global_load_dwordx4 v[242:245], v189, s[70:71] offset:64
	global_load_dwordx4 v[246:249], v189, s[70:71] offset:512
	global_load_dwordx4 v[250:253], v189, s[70:71] offset:576
	v_xor_b32_e32 v174, 16, v170
	v_and_b32_e32 v179, 64, v170
	v_add_u32_e32 v179, 64, v179
	v_xor_b32_e32 v175, 32, v170
	v_cmp_lt_i32_e32 vcc, v174, v179
	s_nop 1
	v_cndmask_b32_e32 v174, v170, v174, vcc
	v_cmp_lt_i32_e32 vcc, v175, v179
	v_lshlrev_b32_e32 v174, 2, v174
	s_nop 1
	v_cndmask_b32_e32 v175, v170, v175, vcc
	v_lshlrev_b32_e32 v175, 2, v175
	v_mov_b32_e32 v180, v188
	v_add_u32_e32 v189, 0x100000, v188
	s_waitcnt vmcnt(15)
	v_pk_add_f32 v[78:79], v[78:79], v[192:193]
	v_pk_add_f32 v[76:77], v[76:77], v[190:191]
	global_store_dwordx4 v180, v[76:79], s[70:71]
	global_load_dwordx4 v[190:193], v189, s[70:71]
	v_mul_f32_e32 v178, v77, v77
	v_mul_f32_e32 v177, v79, v79
	v_fmac_f32_e32 v178, v76, v76
	v_fmac_f32_e32 v177, v78, v78
	v_add_f32_e32 v178, v178, v177
	s_waitcnt vmcnt(16)
	v_pk_add_f32 v[74:75], v[74:75], v[196:197]
	v_pk_add_f32 v[72:73], v[72:73], v[194:195]
	global_store_dwordx4 v180, v[72:75], s[70:71] offset:64
	global_load_dwordx4 v[194:197], v189, s[70:71] offset:64
	v_mul_f32_e32 v176, v73, v73
	v_mul_f32_e32 v177, v75, v75
	v_fmac_f32_e32 v176, v72, v72
	v_fmac_f32_e32 v177, v74, v74
	v_add_f32_e32 v176, v176, v177
	v_add_f32_e32 v178, v178, v176
	s_waitcnt vmcnt(17)
	v_pk_add_f32 v[70:71], v[70:71], v[200:201]
	v_pk_add_f32 v[68:69], v[68:69], v[198:199]
	global_store_dwordx4 v180, v[68:71], s[70:71] offset:512
	global_load_dwordx4 v[198:201], v189, s[70:71] offset:512
	v_mul_f32_e32 v176, v69, v69
	v_mul_f32_e32 v177, v71, v71
	v_fmac_f32_e32 v176, v68, v68
	v_fmac_f32_e32 v177, v70, v70
	v_add_f32_e32 v176, v176, v177
	v_add_f32_e32 v178, v178, v176
	s_waitcnt vmcnt(18)
	v_pk_add_f32 v[66:67], v[66:67], v[204:205]
	v_pk_add_f32 v[64:65], v[64:65], v[202:203]
	global_store_dwordx4 v180, v[64:67], s[70:71] offset:576
	global_load_dwordx4 v[202:205], v189, s[70:71] offset:576
	v_mul_f32_e32 v176, v65, v65
	v_mul_f32_e32 v177, v67, v67
	v_fmac_f32_e32 v176, v64, v64
	v_fmac_f32_e32 v177, v66, v66
	v_add_f32_e32 v176, v176, v177
	v_add_f32_e32 v178, v178, v176
	ds_bpermute_b32 v176, v174, v178
	s_waitcnt lgkmcnt(0)
	v_add_f32_e32 v178, v178, v176
	ds_bpermute_b32 v176, v175, v178
	s_waitcnt lgkmcnt(0)
	v_add_f32_e32 v178, v178, v176
	s_and_saveexec_b64 s[10:11], s[0:1]
	ds_write_b32 v173, v178
	s_or_b64 exec, exec, s[10:11]
	v_add_u32_e32 v180, 0x20000, v188
	v_add_u32_e32 v189, 0x120000, v188
	s_waitcnt vmcnt(19)
	v_pk_add_f32 v[94:95], v[94:95], v[208:209]
	v_pk_add_f32 v[92:93], v[92:93], v[206:207]
	global_store_dwordx4 v180, v[92:95], s[70:71]
	global_load_dwordx4 v[206:209], v189, s[70:71]
	v_mul_f32_e32 v178, v93, v93
	v_mul_f32_e32 v177, v95, v95
	v_fmac_f32_e32 v178, v92, v92
	v_fmac_f32_e32 v177, v94, v94
	v_add_f32_e32 v178, v178, v177
	s_waitcnt vmcnt(20)
	v_pk_add_f32 v[90:91], v[90:91], v[212:213]
	v_pk_add_f32 v[88:89], v[88:89], v[210:211]
	global_store_dwordx4 v180, v[88:91], s[70:71] offset:64
	global_load_dwordx4 v[210:213], v189, s[70:71] offset:64
	v_mul_f32_e32 v176, v89, v89
	v_mul_f32_e32 v177, v91, v91
	v_fmac_f32_e32 v176, v88, v88
	v_fmac_f32_e32 v177, v90, v90
	v_add_f32_e32 v176, v176, v177
	v_add_f32_e32 v178, v178, v176
	s_waitcnt vmcnt(21)
	v_pk_add_f32 v[86:87], v[86:87], v[216:217]
	v_pk_add_f32 v[84:85], v[84:85], v[214:215]
	global_store_dwordx4 v180, v[84:87], s[70:71] offset:512
	global_load_dwordx4 v[214:217], v189, s[70:71] offset:512
	v_mul_f32_e32 v176, v85, v85
	v_mul_f32_e32 v177, v87, v87
	v_fmac_f32_e32 v176, v84, v84
	v_fmac_f32_e32 v177, v86, v86
	v_add_f32_e32 v176, v176, v177
	v_add_f32_e32 v178, v178, v176
	s_waitcnt vmcnt(22)
	v_pk_add_f32 v[82:83], v[82:83], v[220:221]
	v_pk_add_f32 v[80:81], v[80:81], v[218:219]
	global_store_dwordx4 v180, v[80:83], s[70:71] offset:576
	global_load_dwordx4 v[218:221], v189, s[70:71] offset:576
	v_mul_f32_e32 v176, v81, v81
	v_mul_f32_e32 v177, v83, v83
	v_fmac_f32_e32 v176, v80, v80
	v_fmac_f32_e32 v177, v82, v82
	v_add_f32_e32 v176, v176, v177
	v_add_f32_e32 v178, v178, v176
	ds_bpermute_b32 v176, v174, v178
	s_waitcnt lgkmcnt(0)
	v_add_f32_e32 v178, v178, v176
	ds_bpermute_b32 v176, v175, v178
	s_waitcnt lgkmcnt(0)
	v_add_f32_e32 v178, v178, v176
	s_and_saveexec_b64 s[10:11], s[0:1]
	ds_write_b32 v173, v178 offset:256
	s_or_b64 exec, exec, s[10:11]
	v_add_u32_e32 v180, 0x40000, v188
	v_add_u32_e32 v189, 0x140000, v188
	s_waitcnt vmcnt(23)
;     __device__ __forceinline__ void operator()(f32x4 (&acc)[2][2][4][2], const Unit& u, int wr, int wc, int fr, int fq) const {
;     ...
;             for (int m = 0; m < 4; ++m) { const size_t off = (size_t)(row0 + ai * HALF + m * 16) * ldc + col0; float s = 0.f;
; #pragma unroll
;                 for (int bj = 0; bj < 2; ++bj)
; #pragma unroll
;                     for (int n = 0; n < 2; ++n) { const f32x4 b = *(const f32x4*)(base + off + bj * HALF + n * 16); const f32x4 v = b + acc[ai][bj][m][n] * alpha; acc[ai][bj][m][n] = v; *(f32x4*)(out + off + bj * HALF + n * 16) = v;
;                         s += (v[0] * v[0] + v[1] * v[1]) + (v[2] * v[2] + v[3] * v[3]); }
;                 s += __shfl_xor(s, 16); s += __shfl_xor(s, 32);
;                 if (fq == 0) P[(ai * HALF + wr * 64 + m * 16 + fr) * 4 + wc] = s;
;                 if (m & 1) asm volatile("" ::: "memory"); }
	v_pk_add_f32 v[118:119], v[118:119], v[224:225]
	v_pk_add_f32 v[116:117], v[116:117], v[222:223]
	global_store_dwordx4 v180, v[116:119], s[70:71]
	global_load_dwordx4 v[222:225], v189, s[70:71]
	v_mul_f32_e32 v178, v117, v117
	v_mul_f32_e32 v177, v119, v119
	v_fmac_f32_e32 v178, v116, v116
	v_fmac_f32_e32 v177, v118, v118
	v_add_f32_e32 v178, v178, v177
	s_waitcnt vmcnt(24)
	v_pk_add_f32 v[114:115], v[114:115], v[228:229]
	v_pk_add_f32 v[112:113], v[112:113], v[226:227]
	global_store_dwordx4 v180, v[112:115], s[70:71] offset:64
	global_load_dwordx4 v[226:229], v189, s[70:71] offset:64
	v_mul_f32_e32 v176, v113, v113
	v_mul_f32_e32 v177, v115, v115
	v_fmac_f32_e32 v176, v112, v112
	v_fmac_f32_e32 v177, v114, v114
	v_add_f32_e32 v176, v176, v177
	v_add_f32_e32 v178, v178, v176
	s_waitcnt vmcnt(25)
	v_pk_add_f32 v[110:111], v[110:111], v[232:233]
	v_pk_add_f32 v[108:109], v[108:109], v[230:231]
	global_store_dwordx4 v180, v[108:111], s[70:71] offset:512
	global_load_dwordx4 v[230:233], v189, s[70:71] offset:512
	v_mul_f32_e32 v176, v109, v109
	v_mul_f32_e32 v177, v111, v111
	v_fmac_f32_e32 v176, v108, v108
	v_fmac_f32_e32 v177, v110, v110
	v_add_f32_e32 v176, v176, v177
	v_add_f32_e32 v178, v178, v176
	s_waitcnt vmcnt(26)
	v_pk_add_f32 v[98:99], v[98:99], v[236:237]
	v_pk_add_f32 v[96:97], v[96:97], v[234:235]
	global_store_dwordx4 v180, v[96:99], s[70:71] offset:576
	global_load_dwordx4 v[234:237], v189, s[70:71] offset:576
	v_mul_f32_e32 v176, v97, v97
	v_mul_f32_e32 v177, v99, v99
	v_fmac_f32_e32 v176, v96, v96
	v_fmac_f32_e32 v177, v98, v98
	v_add_f32_e32 v176, v176, v177
	v_add_f32_e32 v178, v178, v176
	ds_bpermute_b32 v176, v174, v178
	s_waitcnt lgkmcnt(0)
	v_add_f32_e32 v178, v178, v176
	ds_bpermute_b32 v176, v175, v178
	s_waitcnt lgkmcnt(0)
	v_add_f32_e32 v178, v178, v176
	s_and_saveexec_b64 s[10:11], s[0:1]
	ds_write_b32 v173, v178 offset:512
	s_or_b64 exec, exec, s[10:11]
	v_add_u32_e32 v180, 0x60000, v188
	v_add_u32_e32 v189, 0x160000, v188
	s_waitcnt vmcnt(27)
	v_pk_add_f32 v[126:127], v[126:127], v[240:241]
	v_pk_add_f32 v[124:125], v[124:125], v[238:239]
	global_store_dwordx4 v180, v[124:127], s[70:71]
	global_load_dwordx4 v[238:241], v189, s[70:71]
	v_mul_f32_e32 v178, v125, v125
	v_mul_f32_e32 v177, v127, v127
	v_fmac_f32_e32 v178, v124, v124
	v_fmac_f32_e32 v177, v126, v126
	v_add_f32_e32 v178, v178, v177
	s_waitcnt vmcnt(28)
	v_pk_add_f32 v[122:123], v[122:123], v[244:245]
	v_pk_add_f32 v[120:121], v[120:121], v[242:243]
	global_store_dwordx4 v180, v[120:123], s[70:71] offset:64
	global_load_dwordx4 v[242:245], v189, s[70:71] offset:64
	v_mul_f32_e32 v176, v121, v121
	v_mul_f32_e32 v177, v123, v123
	v_fmac_f32_e32 v176, v120, v120
	v_fmac_f32_e32 v177, v122, v122
	v_add_f32_e32 v176, v176, v177
	v_add_f32_e32 v178, v178, v176
	s_waitcnt vmcnt(29)
	v_pk_add_f32 v[106:107], v[106:107], v[248:249]
	v_pk_add_f32 v[104:105], v[104:105], v[246:247]
	global_store_dwordx4 v180, v[104:107], s[70:71] offset:512
	global_load_dwordx4 v[246:249], v189, s[70:71] offset:512
	v_mul_f32_e32 v176, v105, v105
	v_mul_f32_e32 v177, v107, v107
	v_fmac_f32_e32 v176, v104, v104
	v_fmac_f32_e32 v177, v106, v106
	v_add_f32_e32 v176, v176, v177
	v_add_f32_e32 v178, v178, v176
	s_waitcnt vmcnt(30)
	v_pk_add_f32 v[102:103], v[102:103], v[252:253]
	v_pk_add_f32 v[100:101], v[100:101], v[250:251]
	global_store_dwordx4 v180, v[100:103], s[70:71] offset:576
	global_load_dwordx4 v[250:253], v189, s[70:71] offset:576
	v_mul_f32_e32 v176, v101, v101
	v_mul_f32_e32 v177, v103, v103
	v_fmac_f32_e32 v176, v100, v100
	v_fmac_f32_e32 v177, v102, v102
	v_add_f32_e32 v176, v176, v177
	v_add_f32_e32 v178, v178, v176
	ds_bpermute_b32 v176, v174, v178
	s_waitcnt lgkmcnt(0)
	v_add_f32_e32 v178, v178, v176
	ds_bpermute_b32 v176, v175, v178
	s_waitcnt lgkmcnt(0)
	v_add_f32_e32 v178, v178, v176
	s_and_saveexec_b64 s[10:11], s[0:1]
	ds_write_b32 v173, v178 offset:768
	s_or_b64 exec, exec, s[10:11]
	v_add_u32_e32 v180, 0x100000, v188
	s_waitcnt vmcnt(30)
	v_pk_add_f32 v[62:63], v[62:63], v[192:193]
	v_pk_add_f32 v[60:61], v[60:61], v[190:191]
	global_store_dwordx4 v180, v[60:63], s[70:71]
	v_mul_f32_e32 v178, v61, v61
	v_mul_f32_e32 v177, v63, v63
	v_fmac_f32_e32 v178, v60, v60
	v_fmac_f32_e32 v177, v62, v62
	v_add_f32_e32 v178, v178, v177
	s_waitcnt vmcnt(29)
	v_pk_add_f32 v[58:59], v[58:59], v[196:197]
	v_pk_add_f32 v[56:57], v[56:57], v[194:195]
	global_store_dwordx4 v180, v[56:59], s[70:71] offset:64
	v_mul_f32_e32 v176, v57, v57
	v_mul_f32_e32 v177, v59, v59
	v_fmac_f32_e32 v176, v56, v56
	v_fmac_f32_e32 v177, v58, v58
	v_add_f32_e32 v176, v176, v177
	v_add_f32_e32 v178, v178, v176
	s_waitcnt vmcnt(28)
	v_pk_add_f32 v[54:55], v[54:55], v[200:201]
	v_pk_add_f32 v[52:53], v[52:53], v[198:199]
	global_store_dwordx4 v180, v[52:55], s[70:71] offset:512
	v_mul_f32_e32 v176, v53, v53
	v_mul_f32_e32 v177, v55, v55
	v_fmac_f32_e32 v176, v52, v52
	v_fmac_f32_e32 v177, v54, v54
	v_add_f32_e32 v176, v176, v177
	v_add_f32_e32 v178, v178, v176
	s_waitcnt vmcnt(27)
	v_pk_add_f32 v[50:51], v[50:51], v[204:205]
	v_pk_add_f32 v[48:49], v[48:49], v[202:203]
	global_store_dwordx4 v180, v[48:51], s[70:71] offset:576
	v_mul_f32_e32 v176, v49, v49
	v_mul_f32_e32 v177, v51, v51
	v_fmac_f32_e32 v176, v48, v48
	v_fmac_f32_e32 v177, v50, v50
	v_add_f32_e32 v176, v176, v177
	v_add_f32_e32 v178, v178, v176
	ds_bpermute_b32 v176, v174, v178
	s_waitcnt lgkmcnt(0)
	v_add_f32_e32 v178, v178, v176
	ds_bpermute_b32 v176, v175, v178
	s_waitcnt lgkmcnt(0)
	v_add_f32_e32 v178, v178, v176
	s_and_saveexec_b64 s[10:11], s[0:1]
	ds_write_b32 v171, v178
	s_or_b64 exec, exec, s[10:11]
	v_add_u32_e32 v180, 0x120000, v188
	s_waitcnt vmcnt(26)
;     __device__ __forceinline__ void operator()(f32x4 (&acc)[2][2][4][2], const Unit& u, int wr, int wc, int fr, int fq) const {
;     ...
;             for (int m = 0; m < 4; ++m) { const size_t off = (size_t)(row0 + ai * HALF + m * 16) * ldc + col0; float s = 0.f;
; #pragma unroll
;                 for (int bj = 0; bj < 2; ++bj)
; #pragma unroll
;                     for (int n = 0; n < 2; ++n) { const f32x4 b = *(const f32x4*)(base + off + bj * HALF + n * 16); const f32x4 v = b + acc[ai][bj][m][n] * alpha; acc[ai][bj][m][n] = v; *(f32x4*)(out + off + bj * HALF + n * 16) = v;
;                         s += (v[0] * v[0] + v[1] * v[1]) + (v[2] * v[2] + v[3] * v[3]); }
;                 s += __shfl_xor(s, 16); s += __shfl_xor(s, 32);
;                 if (fq == 0) P[(ai * HALF + wr * 64 + m * 16 + fr) * 4 + wc] = s;
;                 if (m & 1) asm volatile("" ::: "memory"); }
;         asm volatile("s_waitcnt lgkmcnt(0)" ::: "memory"); __builtin_amdgcn_s_barrier(); asm volatile("" ::: "memory");
;         const int row = wid * 32 + (lane & 31);
;         float* prow = part + ((size_t)(u.pm * BM + row)) * 8;
;         if (lane < 32) { const float tot = (P[row * 4] + P[row * 4 + 1]) + (P[row * 4 + 2] + P[row * 4 + 3]); __hip_atomic_store(prow + u.pn, tot, __ATOMIC_RELAXED, __HIP_MEMORY_SCOPE_AGENT); }
	v_pk_add_f32 v[46:47], v[46:47], v[208:209]
	v_pk_add_f32 v[44:45], v[44:45], v[206:207]
	global_store_dwordx4 v180, v[44:47], s[70:71]
	v_mul_f32_e32 v178, v45, v45
	v_mul_f32_e32 v177, v47, v47
	v_fmac_f32_e32 v178, v44, v44
	v_fmac_f32_e32 v177, v46, v46
	v_add_f32_e32 v178, v178, v177
	s_waitcnt vmcnt(25)
	v_pk_add_f32 v[42:43], v[42:43], v[212:213]
	v_pk_add_f32 v[40:41], v[40:41], v[210:211]
	global_store_dwordx4 v180, v[40:43], s[70:71] offset:64
	v_mul_f32_e32 v176, v41, v41
	v_mul_f32_e32 v177, v43, v43
	v_fmac_f32_e32 v176, v40, v40
	v_fmac_f32_e32 v177, v42, v42
	v_add_f32_e32 v176, v176, v177
	v_add_f32_e32 v178, v178, v176
	s_waitcnt vmcnt(24)
	v_pk_add_f32 v[38:39], v[38:39], v[216:217]
	v_pk_add_f32 v[36:37], v[36:37], v[214:215]
	global_store_dwordx4 v180, v[36:39], s[70:71] offset:512
	v_mul_f32_e32 v176, v37, v37
	v_mul_f32_e32 v177, v39, v39
	v_fmac_f32_e32 v176, v36, v36
	v_fmac_f32_e32 v177, v38, v38
	v_add_f32_e32 v176, v176, v177
	v_add_f32_e32 v178, v178, v176
	s_waitcnt vmcnt(23)
	v_pk_add_f32 v[34:35], v[34:35], v[220:221]
	v_pk_add_f32 v[32:33], v[32:33], v[218:219]
	global_store_dwordx4 v180, v[32:35], s[70:71] offset:576
	v_mul_f32_e32 v176, v33, v33
	v_mul_f32_e32 v177, v35, v35
	v_fmac_f32_e32 v176, v32, v32
	v_fmac_f32_e32 v177, v34, v34
	v_add_f32_e32 v176, v176, v177
	v_add_f32_e32 v178, v178, v176
	ds_bpermute_b32 v176, v174, v178
	s_waitcnt lgkmcnt(0)
	v_add_f32_e32 v178, v178, v176
	ds_bpermute_b32 v176, v175, v178
	s_waitcnt lgkmcnt(0)
	v_add_f32_e32 v178, v178, v176
	s_and_saveexec_b64 s[10:11], s[0:1]
	ds_write_b32 v173, v178 offset:2304
	s_or_b64 exec, exec, s[10:11]
	v_add_u32_e32 v180, 0x140000, v188
	s_waitcnt vmcnt(22)
	v_pk_add_f32 v[30:31], v[30:31], v[224:225]
	v_pk_add_f32 v[28:29], v[28:29], v[222:223]
	global_store_dwordx4 v180, v[28:31], s[70:71]
	v_mul_f32_e32 v178, v29, v29
	v_mul_f32_e32 v177, v31, v31
	v_fmac_f32_e32 v178, v28, v28
	v_fmac_f32_e32 v177, v30, v30
	v_add_f32_e32 v178, v178, v177
	s_waitcnt vmcnt(21)
	v_pk_add_f32 v[26:27], v[26:27], v[228:229]
	v_pk_add_f32 v[24:25], v[24:25], v[226:227]
	global_store_dwordx4 v180, v[24:27], s[70:71] offset:64
	v_mul_f32_e32 v176, v25, v25
	v_mul_f32_e32 v177, v27, v27
	v_fmac_f32_e32 v176, v24, v24
	v_fmac_f32_e32 v177, v26, v26
	v_add_f32_e32 v176, v176, v177
	v_add_f32_e32 v178, v178, v176
	s_waitcnt vmcnt(20)
	v_pk_add_f32 v[22:23], v[22:23], v[232:233]
	v_pk_add_f32 v[20:21], v[20:21], v[230:231]
	global_store_dwordx4 v180, v[20:23], s[70:71] offset:512
	v_mul_f32_e32 v176, v21, v21
	v_mul_f32_e32 v177, v23, v23
	v_fmac_f32_e32 v176, v20, v20
	v_fmac_f32_e32 v177, v22, v22
	v_add_f32_e32 v176, v176, v177
	v_add_f32_e32 v178, v178, v176
	s_waitcnt vmcnt(19)
	v_pk_add_f32 v[18:19], v[18:19], v[236:237]
	v_pk_add_f32 v[16:17], v[16:17], v[234:235]
	global_store_dwordx4 v180, v[16:19], s[70:71] offset:576
	v_mul_f32_e32 v176, v17, v17
	v_mul_f32_e32 v177, v19, v19
	v_fmac_f32_e32 v176, v16, v16
	v_fmac_f32_e32 v177, v18, v18
	v_add_f32_e32 v176, v176, v177
	v_add_f32_e32 v178, v178, v176
	ds_bpermute_b32 v176, v174, v178
	s_waitcnt lgkmcnt(0)
	v_add_f32_e32 v178, v178, v176
	ds_bpermute_b32 v176, v175, v178
	s_waitcnt lgkmcnt(0)
	v_add_f32_e32 v178, v178, v176
	s_and_saveexec_b64 s[10:11], s[0:1]
	ds_write_b32 v173, v178 offset:2560
	s_or_b64 exec, exec, s[10:11]
	v_add_u32_e32 v180, 0x160000, v188
	s_waitcnt vmcnt(18)
	v_pk_add_f32 v[14:15], v[14:15], v[240:241]
	v_pk_add_f32 v[12:13], v[12:13], v[238:239]
	global_store_dwordx4 v180, v[12:15], s[70:71]
	v_mul_f32_e32 v178, v13, v13
	v_mul_f32_e32 v177, v15, v15
	v_fmac_f32_e32 v178, v12, v12
	v_fmac_f32_e32 v177, v14, v14
	v_add_f32_e32 v178, v178, v177
	s_waitcnt vmcnt(17)
	v_pk_add_f32 v[10:11], v[10:11], v[244:245]
	v_pk_add_f32 v[8:9], v[8:9], v[242:243]
	global_store_dwordx4 v180, v[8:11], s[70:71] offset:64
	v_mul_f32_e32 v176, v9, v9
	v_mul_f32_e32 v177, v11, v11
	v_fmac_f32_e32 v176, v8, v8
	v_fmac_f32_e32 v177, v10, v10
	v_add_f32_e32 v176, v176, v177
	v_add_f32_e32 v178, v178, v176
	s_waitcnt vmcnt(16)
	v_pk_add_f32 v[6:7], v[6:7], v[248:249]
	v_pk_add_f32 v[4:5], v[4:5], v[246:247]
	global_store_dwordx4 v180, v[4:7], s[70:71] offset:512
	v_mul_f32_e32 v176, v5, v5
	v_mul_f32_e32 v177, v7, v7
	v_fmac_f32_e32 v176, v4, v4
	v_fmac_f32_e32 v177, v6, v6
	v_add_f32_e32 v176, v176, v177
	v_add_f32_e32 v178, v178, v176
	s_waitcnt vmcnt(15)
	v_pk_add_f32 v[2:3], v[2:3], v[252:253]
	v_pk_add_f32 v[0:1], v[0:1], v[250:251]
	global_store_dwordx4 v180, v[0:3], s[70:71] offset:576
	v_mul_f32_e32 v176, v1, v1
	v_mul_f32_e32 v177, v3, v3
	v_fmac_f32_e32 v176, v0, v0
	v_fmac_f32_e32 v177, v2, v2
	v_add_f32_e32 v176, v176, v177
	v_add_f32_e32 v178, v178, v176
	ds_bpermute_b32 v176, v174, v178
	s_waitcnt lgkmcnt(0)
	v_add_f32_e32 v178, v178, v176
	ds_bpermute_b32 v176, v175, v178
	s_waitcnt lgkmcnt(0)
	v_add_f32_e32 v178, v178, v176
	s_and_saveexec_b64 s[10:11], s[0:1]
	ds_write_b32 v173, v178 offset:2816
	s_or_b64 exec, exec, s[10:11]
	global_load_dwordx4 v[190:193], v[132:133], off
	global_load_dwordx4 v[194:197], v[132:133], off offset:64
	global_load_dwordx4 v[198:201], v[132:133], off offset:512
	global_load_dwordx4 v[202:205], v[132:133], off offset:576
	v_add_u32_e32 v146, s49, v151
	s_waitcnt lgkmcnt(0)
	s_barrier
	s_waitcnt lgkmcnt(0)
	v_ashrrev_i32_e32 v147, 31, v146
	v_lshlrev_b64 v[146:147], 5, v[146:147]
	v_lshl_add_u64 v[146:147], s[24:25], 0, v[146:147]
	s_and_saveexec_b64 s[10:11], s[8:9]
	s_cbranch_execz .LBB0_581
	ds_read_b128 v[174:177], v172
	s_lshl_b32 s34, s3, 2
	s_waitcnt lgkmcnt(0)
	v_mov_b32_e32 v178, v175
	v_mov_b32_e32 v179, v176
	v_mov_b32_e32 v175, v177
	v_pk_add_f32 v[174:175], v[178:179], v[174:175]
	v_lshl_add_u64 v[176:177], v[146:147], 0, s[34:35]
	v_pk_add_f32 v[174:175], v[174:175], v[174:175] op_sel:[0,1] op_sel_hi:[1,0]
	global_store_dword v[176:177], v174, off sc1

;     __device__ __forceinline__ void operator()(f32x4 (&acc)[2][2][4][2], const Unit& u, int wr, int wc, int fr, int fq) const {
;     ...
;             for (int m = 0; m < 4; ++m) { const size_t off = (size_t)(row0 + ai * HALF + m * 16) * ldc + col0; float s = 0.f;
; #pragma unroll
;                 for (int bj = 0; bj < 2; ++bj)
; #pragma unroll
;                     for (int n = 0; n < 2; ++n) { const f32x4 b = *(const f32x4*)(base + off + bj * HALF + n * 16); const f32x4 v = b + acc[ai][bj][m][n] * alpha; acc[ai][bj][m][n] = v;
;                         s += (v[0] * v[0] + v[1] * v[1]) + (v[2] * v[2] + v[3] * v[3]); }
;                 s += __shfl_xor(s, 16); s += __shfl_xor(s, 32);
;                 if (fq == 0) P[(ai * HALF + wr * 64 + m * 16 + fr) * 4 + wc] = s;
;                 if (m & 1) asm volatile("" ::: "memory"); }
.LBB0_652:
	s_lshl_b32 s42, s64, 8
	v_add_u32_e32 v142, s42, v146
	v_subrev_u32_e32 v179, s70, v132
	v_ashrrev_i32_e32 v143, 31, v142
	v_lshl_add_u32 v179, v142, 13, v179
	v_lshlrev_b64 v[140:141], 13, v[142:143]
	v_lshl_add_u64 v[140:141], v[132:133], 0, v[140:141]
	v_mov_b32_e32 v178, v179
	global_load_dwordx4 v[196:199], v178, s[70:71]
	global_load_dwordx4 v[200:203], v178, s[70:71] offset:64
	global_load_dwordx4 v[204:207], v178, s[70:71] offset:512
	global_load_dwordx4 v[208:211], v178, s[70:71] offset:576
	v_add_u32_e32 v178, 0x20000, v179
	global_load_dwordx4 v[212:215], v178, s[70:71]
	global_load_dwordx4 v[216:219], v178, s[70:71] offset:64
	global_load_dwordx4 v[220:223], v178, s[70:71] offset:512
	global_load_dwordx4 v[224:227], v178, s[70:71] offset:576
	v_add_u32_e32 v178, 0x40000, v179
	global_load_dwordx4 v[228:231], v178, s[70:71]
	global_load_dwordx4 v[232:235], v178, s[70:71] offset:64
	global_load_dwordx4 v[236:239], v178, s[70:71] offset:512
	global_load_dwordx4 v[240:243], v178, s[70:71] offset:576
	v_xor_b32_e32 v175, 16, v168
	v_and_b32_e32 v182, 64, v168
	v_add_u32_e32 v182, 64, v182
	v_xor_b32_e32 v176, 32, v168
	v_cmp_lt_i32_e32 vcc, v175, v182
	s_nop 1
	v_cndmask_b32_e32 v175, v168, v175, vcc
	v_cmp_lt_i32_e32 vcc, v176, v182
	v_lshlrev_b32_e32 v175, 2, v175
	s_nop 1
	v_cndmask_b32_e32 v176, v168, v176, vcc
	v_lshlrev_b32_e32 v176, 2, v176
	v_add_u32_e32 v178, 0x60000, v179
	s_waitcnt vmcnt(11)
	v_pk_fma_f32 v[126:127], v[126:127], 0.5, v[198:199] op_sel_hi:[1,0,1]
	v_pk_fma_f32 v[124:125], v[124:125], 0.5, v[196:197] op_sel_hi:[1,0,1]
	global_load_dwordx4 v[196:199], v178, s[70:71]
	v_mul_f32_e32 v181, v125, v125
	v_mul_f32_e32 v180, v127, v127
	v_fmac_f32_e32 v181, v124, v124
	v_fmac_f32_e32 v180, v126, v126
	v_add_f32_e32 v181, v181, v180
	s_waitcnt vmcnt(11)
	v_pk_fma_f32 v[122:123], v[122:123], 0.5, v[202:203] op_sel_hi:[1,0,1]
	v_pk_fma_f32 v[120:121], v[120:121], 0.5, v[200:201] op_sel_hi:[1,0,1]
	global_load_dwordx4 v[200:203], v178, s[70:71] offset:64
	v_mul_f32_e32 v177, v121, v121
	v_mul_f32_e32 v180, v123, v123
	v_fmac_f32_e32 v177, v120, v120
	v_fmac_f32_e32 v180, v122, v122
	v_add_f32_e32 v177, v177, v180
	v_add_f32_e32 v181, v181, v177
	s_waitcnt vmcnt(11)
	v_pk_fma_f32 v[118:119], v[118:119], 0.5, v[206:207] op_sel_hi:[1,0,1]
	v_pk_fma_f32 v[116:117], v[116:117], 0.5, v[204:205] op_sel_hi:[1,0,1]
	global_load_dwordx4 v[204:207], v178, s[70:71] offset:512
	v_mul_f32_e32 v177, v117, v117
	v_mul_f32_e32 v180, v119, v119
	v_fmac_f32_e32 v177, v116, v116
	v_fmac_f32_e32 v180, v118, v118
	v_add_f32_e32 v177, v177, v180
	v_add_f32_e32 v181, v181, v177
	s_waitcnt vmcnt(11)
	v_pk_fma_f32 v[114:115], v[114:115], 0.5, v[210:211] op_sel_hi:[1,0,1]
	v_pk_fma_f32 v[112:113], v[112:113], 0.5, v[208:209] op_sel_hi:[1,0,1]
	global_load_dwordx4 v[208:211], v178, s[70:71] offset:576
	v_mul_f32_e32 v177, v113, v113
	v_mul_f32_e32 v180, v115, v115
	v_fmac_f32_e32 v177, v112, v112
	v_fmac_f32_e32 v180, v114, v114
	v_add_f32_e32 v177, v177, v180
	v_add_f32_e32 v181, v181, v177
	ds_bpermute_b32 v177, v175, v181
	s_waitcnt lgkmcnt(0)
	v_add_f32_e32 v181, v181, v177
	ds_bpermute_b32 v177, v176, v181
	s_waitcnt lgkmcnt(0)
	v_add_f32_e32 v181, v181, v177
	s_and_saveexec_b64 s[8:9], s[0:1]
	ds_write_b32 v174, v181
	s_or_b64 exec, exec, s[8:9]
	v_add_u32_e32 v178, 0x100000, v179
	s_waitcnt vmcnt(11)
	v_pk_fma_f32 v[110:111], v[110:111], 0.5, v[214:215] op_sel_hi:[1,0,1]
	v_pk_fma_f32 v[108:109], v[108:109], 0.5, v[212:213] op_sel_hi:[1,0,1]
	global_load_dwordx4 v[212:215], v178, s[70:71]
	v_mul_f32_e32 v181, v109, v109
	v_mul_f32_e32 v180, v111, v111
	v_fmac_f32_e32 v181, v108, v108
	v_fmac_f32_e32 v180, v110, v110
	v_add_f32_e32 v181, v181, v180
	s_waitcnt vmcnt(11)
	v_pk_fma_f32 v[106:107], v[106:107], 0.5, v[218:219] op_sel_hi:[1,0,1]
	v_pk_fma_f32 v[104:105], v[104:105], 0.5, v[216:217] op_sel_hi:[1,0,1]
	global_load_dwordx4 v[216:219], v178, s[70:71] offset:64
	v_mul_f32_e32 v177, v105, v105
	v_mul_f32_e32 v180, v107, v107
	v_fmac_f32_e32 v177, v104, v104
	v_fmac_f32_e32 v180, v106, v106
	v_add_f32_e32 v177, v177, v180
	v_add_f32_e32 v181, v181, v177
	s_waitcnt vmcnt(11)
	v_pk_fma_f32 v[102:103], v[102:103], 0.5, v[222:223] op_sel_hi:[1,0,1]
	v_pk_fma_f32 v[100:101], v[100:101], 0.5, v[220:221] op_sel_hi:[1,0,1]
	global_load_dwordx4 v[220:223], v178, s[70:71] offset:512
	v_mul_f32_e32 v177, v101, v101
	v_mul_f32_e32 v180, v103, v103
	v_fmac_f32_e32 v177, v100, v100
	v_fmac_f32_e32 v180, v102, v102
	v_add_f32_e32 v177, v177, v180
	v_add_f32_e32 v181, v181, v177
	s_waitcnt vmcnt(11)
	v_pk_fma_f32 v[98:99], v[98:99], 0.5, v[226:227] op_sel_hi:[1,0,1]
	v_pk_fma_f32 v[96:97], v[96:97], 0.5, v[224:225] op_sel_hi:[1,0,1]
	global_load_dwordx4 v[224:227], v178, s[70:71] offset:576
	v_mul_f32_e32 v177, v97, v97
	v_mul_f32_e32 v180, v99, v99
	v_fmac_f32_e32 v177, v96, v96
	v_fmac_f32_e32 v180, v98, v98
	v_add_f32_e32 v177, v177, v180
	v_add_f32_e32 v181, v181, v177
	ds_bpermute_b32 v177, v175, v181
	s_waitcnt lgkmcnt(0)
	v_add_f32_e32 v181, v181, v177
	ds_bpermute_b32 v177, v176, v181
	s_waitcnt lgkmcnt(0)
	v_add_f32_e32 v181, v181, v177
	s_and_saveexec_b64 s[8:9], s[0:1]
	ds_write_b32 v174, v181 offset:256
	s_or_b64 exec, exec, s[8:9]
	v_add_u32_e32 v178, 0x120000, v179
	s_waitcnt vmcnt(11)
	v_pk_fma_f32 v[94:95], v[94:95], 0.5, v[230:231] op_sel_hi:[1,0,1]
	v_pk_fma_f32 v[92:93], v[92:93], 0.5, v[228:229] op_sel_hi:[1,0,1]
	global_load_dwordx4 v[228:231], v178, s[70:71]
	v_mul_f32_e32 v181, v93, v93
	v_mul_f32_e32 v180, v95, v95
	v_fmac_f32_e32 v181, v92, v92
	v_fmac_f32_e32 v180, v94, v94
	v_add_f32_e32 v181, v181, v180
	s_waitcnt vmcnt(11)
;     __device__ __forceinline__ void operator()(f32x4 (&acc)[2][2][4][2], const Unit& u, int wr, int wc, int fr, int fq) const {
;     ...
;             for (int m = 0; m < 4; ++m) { const size_t off = (size_t)(row0 + ai * HALF + m * 16) * ldc + col0; float s = 0.f;
; #pragma unroll
;                 for (int bj = 0; bj < 2; ++bj)
; #pragma unroll
;                     for (int n = 0; n < 2; ++n) { const f32x4 b = *(const f32x4*)(base + off + bj * HALF + n * 16); const f32x4 v = b + acc[ai][bj][m][n] * alpha; acc[ai][bj][m][n] = v;
;                         s += (v[0] * v[0] + v[1] * v[1]) + (v[2] * v[2] + v[3] * v[3]); }
;                 s += __shfl_xor(s, 16); s += __shfl_xor(s, 32);
;                 if (fq == 0) P[(ai * HALF + wr * 64 + m * 16 + fr) * 4 + wc] = s;
;                 if (m & 1) asm volatile("" ::: "memory"); }
	v_pk_fma_f32 v[90:91], v[90:91], 0.5, v[234:235] op_sel_hi:[1,0,1]
	v_pk_fma_f32 v[88:89], v[88:89], 0.5, v[232:233] op_sel_hi:[1,0,1]
	global_load_dwordx4 v[232:235], v178, s[70:71] offset:64
	v_mul_f32_e32 v177, v89, v89
	v_mul_f32_e32 v180, v91, v91
	v_fmac_f32_e32 v177, v88, v88
	v_fmac_f32_e32 v180, v90, v90
	v_add_f32_e32 v177, v177, v180
	v_add_f32_e32 v181, v181, v177
	s_waitcnt vmcnt(11)
	v_pk_fma_f32 v[86:87], v[86:87], 0.5, v[238:239] op_sel_hi:[1,0,1]
	v_pk_fma_f32 v[84:85], v[84:85], 0.5, v[236:237] op_sel_hi:[1,0,1]
	global_load_dwordx4 v[236:239], v178, s[70:71] offset:512
	v_mul_f32_e32 v177, v85, v85
	v_mul_f32_e32 v180, v87, v87
	v_fmac_f32_e32 v177, v84, v84
	v_fmac_f32_e32 v180, v86, v86
	v_add_f32_e32 v177, v177, v180
	v_add_f32_e32 v181, v181, v177
	s_waitcnt vmcnt(11)
	v_pk_fma_f32 v[82:83], v[82:83], 0.5, v[242:243] op_sel_hi:[1,0,1]
	v_pk_fma_f32 v[80:81], v[80:81], 0.5, v[240:241] op_sel_hi:[1,0,1]
	global_load_dwordx4 v[240:243], v178, s[70:71] offset:576
	v_mul_f32_e32 v177, v81, v81
	v_mul_f32_e32 v180, v83, v83
	v_fmac_f32_e32 v177, v80, v80
	v_fmac_f32_e32 v180, v82, v82
	v_add_f32_e32 v177, v177, v180
	v_add_f32_e32 v181, v181, v177
	ds_bpermute_b32 v177, v175, v181
	s_waitcnt lgkmcnt(0)
	v_add_f32_e32 v181, v181, v177
	ds_bpermute_b32 v177, v176, v181
	s_waitcnt lgkmcnt(0)
	v_add_f32_e32 v181, v181, v177
	s_and_saveexec_b64 s[8:9], s[0:1]
	ds_write_b32 v174, v181 offset:512
	s_or_b64 exec, exec, s[8:9]
	v_add_u32_e32 v178, 0x140000, v179
	s_waitcnt vmcnt(11)
	v_pk_fma_f32 v[78:79], v[78:79], 0.5, v[198:199] op_sel_hi:[1,0,1]
	v_pk_fma_f32 v[76:77], v[76:77], 0.5, v[196:197] op_sel_hi:[1,0,1]
	global_load_dwordx4 v[196:199], v178, s[70:71]
	v_mul_f32_e32 v181, v77, v77
	v_mul_f32_e32 v180, v79, v79
	v_fmac_f32_e32 v181, v76, v76
	v_fmac_f32_e32 v180, v78, v78
	v_add_f32_e32 v181, v181, v180
	s_waitcnt vmcnt(11)
	v_pk_fma_f32 v[74:75], v[74:75], 0.5, v[202:203] op_sel_hi:[1,0,1]
	v_pk_fma_f32 v[72:73], v[72:73], 0.5, v[200:201] op_sel_hi:[1,0,1]
	global_load_dwordx4 v[200:203], v178, s[70:71] offset:64
	v_mul_f32_e32 v177, v73, v73
	v_mul_f32_e32 v180, v75, v75
	v_fmac_f32_e32 v177, v72, v72
	v_fmac_f32_e32 v180, v74, v74
	v_add_f32_e32 v177, v177, v180
	v_add_f32_e32 v181, v181, v177
	s_waitcnt vmcnt(11)
	v_pk_fma_f32 v[70:71], v[70:71], 0.5, v[206:207] op_sel_hi:[1,0,1]
	v_pk_fma_f32 v[68:69], v[68:69], 0.5, v[204:205] op_sel_hi:[1,0,1]
	global_load_dwordx4 v[204:207], v178, s[70:71] offset:512
	v_mul_f32_e32 v177, v69, v69
	v_mul_f32_e32 v180, v71, v71
	v_fmac_f32_e32 v177, v68, v68
	v_fmac_f32_e32 v180, v70, v70
	v_add_f32_e32 v177, v177, v180
	v_add_f32_e32 v181, v181, v177
	s_waitcnt vmcnt(11)
	v_pk_fma_f32 v[66:67], v[66:67], 0.5, v[210:211] op_sel_hi:[1,0,1]
	v_pk_fma_f32 v[64:65], v[64:65], 0.5, v[208:209] op_sel_hi:[1,0,1]
	global_load_dwordx4 v[208:211], v178, s[70:71] offset:576
	v_mul_f32_e32 v177, v65, v65
	v_mul_f32_e32 v180, v67, v67
	v_fmac_f32_e32 v177, v64, v64
	v_fmac_f32_e32 v180, v66, v66
	v_add_f32_e32 v177, v177, v180
	v_add_f32_e32 v181, v181, v177
	ds_bpermute_b32 v177, v175, v181
	s_waitcnt lgkmcnt(0)
	v_add_f32_e32 v181, v181, v177
	ds_bpermute_b32 v177, v176, v181
	s_waitcnt lgkmcnt(0)
	v_add_f32_e32 v181, v181, v177
	s_and_saveexec_b64 s[8:9], s[0:1]
	ds_write_b32 v174, v181 offset:768
	s_or_b64 exec, exec, s[8:9]
	v_add_u32_e32 v178, 0x160000, v179
	s_waitcnt vmcnt(11)
	v_pk_fma_f32 v[62:63], v[62:63], 0.5, v[214:215] op_sel_hi:[1,0,1]
	v_pk_fma_f32 v[60:61], v[60:61], 0.5, v[212:213] op_sel_hi:[1,0,1]
	global_load_dwordx4 v[212:215], v178, s[70:71]
	v_mul_f32_e32 v181, v61, v61
	v_mul_f32_e32 v180, v63, v63
	v_fmac_f32_e32 v181, v60, v60
	v_fmac_f32_e32 v180, v62, v62
	v_add_f32_e32 v181, v181, v180
	s_waitcnt vmcnt(11)
	v_pk_fma_f32 v[58:59], v[58:59], 0.5, v[218:219] op_sel_hi:[1,0,1]
	v_pk_fma_f32 v[56:57], v[56:57], 0.5, v[216:217] op_sel_hi:[1,0,1]
	global_load_dwordx4 v[216:219], v178, s[70:71] offset:64
	v_mul_f32_e32 v177, v57, v57
	v_mul_f32_e32 v180, v59, v59
	v_fmac_f32_e32 v177, v56, v56
	v_fmac_f32_e32 v180, v58, v58
	v_add_f32_e32 v177, v177, v180
	v_add_f32_e32 v181, v181, v177
	s_waitcnt vmcnt(11)
	v_pk_fma_f32 v[54:55], v[54:55], 0.5, v[222:223] op_sel_hi:[1,0,1]
	v_pk_fma_f32 v[52:53], v[52:53], 0.5, v[220:221] op_sel_hi:[1,0,1]
	global_load_dwordx4 v[220:223], v178, s[70:71] offset:512
	v_mul_f32_e32 v177, v53, v53
	v_mul_f32_e32 v180, v55, v55
	v_fmac_f32_e32 v177, v52, v52
	v_fmac_f32_e32 v180, v54, v54
	v_add_f32_e32 v177, v177, v180
	v_add_f32_e32 v181, v181, v177
	s_waitcnt vmcnt(11)
	v_pk_fma_f32 v[50:51], v[50:51], 0.5, v[226:227] op_sel_hi:[1,0,1]
	v_pk_fma_f32 v[48:49], v[48:49], 0.5, v[224:225] op_sel_hi:[1,0,1]
	global_load_dwordx4 v[224:227], v178, s[70:71] offset:576
	v_mul_f32_e32 v177, v49, v49
	v_mul_f32_e32 v180, v51, v51
	v_fmac_f32_e32 v177, v48, v48
	v_fmac_f32_e32 v180, v50, v50
	v_add_f32_e32 v177, v177, v180
	v_add_f32_e32 v181, v181, v177
	ds_bpermute_b32 v177, v175, v181
	s_waitcnt lgkmcnt(0)
	v_add_f32_e32 v181, v181, v177
	ds_bpermute_b32 v177, v176, v181
	s_waitcnt lgkmcnt(0)
	v_add_f32_e32 v181, v181, v177
	s_and_saveexec_b64 s[8:9], s[0:1]
	ds_write_b32 v169, v181
	s_or_b64 exec, exec, s[8:9]
	s_waitcnt vmcnt(11)
	v_pk_fma_f32 v[46:47], v[46:47], 0.5, v[230:231] op_sel_hi:[1,0,1]
	v_pk_fma_f32 v[44:45], v[44:45], 0.5, v[228:229] op_sel_hi:[1,0,1]
	v_mul_f32_e32 v181, v45, v45
	v_mul_f32_e32 v180, v47, v47
	v_fmac_f32_e32 v181, v44, v44
	v_fmac_f32_e32 v180, v46, v46
	v_add_f32_e32 v181, v181, v180
	s_waitcnt vmcnt(10)
;     __device__ __forceinline__ void operator()(f32x4 (&acc)[2][2][4][2], const Unit& u, int wr, int wc, int fr, int fq) const {
;     ...
;             for (int m = 0; m < 4; ++m) { const size_t off = (size_t)(row0 + ai * HALF + m * 16) * ldc + col0; float s = 0.f;
; #pragma unroll
;                 for (int bj = 0; bj < 2; ++bj)
; #pragma unroll
;                     for (int n = 0; n < 2; ++n) { const f32x4 b = *(const f32x4*)(base + off + bj * HALF + n * 16); const f32x4 v = b + acc[ai][bj][m][n] * alpha; acc[ai][bj][m][n] = v;
;                         s += (v[0] * v[0] + v[1] * v[1]) + (v[2] * v[2] + v[3] * v[3]); }
;                 s += __shfl_xor(s, 16); s += __shfl_xor(s, 32);
;                 if (fq == 0) P[(ai * HALF + wr * 64 + m * 16 + fr) * 4 + wc] = s;
;                 if (m & 1) asm volatile("" ::: "memory"); }
;         asm volatile("s_waitcnt lgkmcnt(0)" ::: "memory"); __builtin_amdgcn_s_barrier(); asm volatile("" ::: "memory");
;         const int row = wid * 32 + (lane & 31);
;         float* prow = part + ((size_t)(u.pm * BM + row)) * 8;
;         if (lane < 32) { const float tot = (P[row * 4] + P[row * 4 + 1]) + (P[row * 4 + 2] + P[row * 4 + 3]); __hip_atomic_store(prow + u.pn, tot, __ATOMIC_RELAXED, __HIP_MEMORY_SCOPE_AGENT); }
	v_pk_fma_f32 v[42:43], v[42:43], 0.5, v[234:235] op_sel_hi:[1,0,1]
	v_pk_fma_f32 v[40:41], v[40:41], 0.5, v[232:233] op_sel_hi:[1,0,1]
	v_mul_f32_e32 v177, v41, v41
	v_mul_f32_e32 v180, v43, v43
	v_fmac_f32_e32 v177, v40, v40
	v_fmac_f32_e32 v180, v42, v42
	v_add_f32_e32 v177, v177, v180
	v_add_f32_e32 v181, v181, v177
	s_waitcnt vmcnt(9)
	v_pk_fma_f32 v[38:39], v[38:39], 0.5, v[238:239] op_sel_hi:[1,0,1]
	v_pk_fma_f32 v[36:37], v[36:37], 0.5, v[236:237] op_sel_hi:[1,0,1]
	v_mul_f32_e32 v177, v37, v37
	v_mul_f32_e32 v180, v39, v39
	v_fmac_f32_e32 v177, v36, v36
	v_fmac_f32_e32 v180, v38, v38
	v_add_f32_e32 v177, v177, v180
	v_add_f32_e32 v181, v181, v177
	s_waitcnt vmcnt(8)
	v_pk_fma_f32 v[34:35], v[34:35], 0.5, v[242:243] op_sel_hi:[1,0,1]
	v_pk_fma_f32 v[32:33], v[32:33], 0.5, v[240:241] op_sel_hi:[1,0,1]
	v_mul_f32_e32 v177, v33, v33
	v_mul_f32_e32 v180, v35, v35
	v_fmac_f32_e32 v177, v32, v32
	v_fmac_f32_e32 v180, v34, v34
	v_add_f32_e32 v177, v177, v180
	v_add_f32_e32 v181, v181, v177
	ds_bpermute_b32 v177, v175, v181
	s_waitcnt lgkmcnt(0)
	v_add_f32_e32 v181, v181, v177
	ds_bpermute_b32 v177, v176, v181
	s_waitcnt lgkmcnt(0)
	v_add_f32_e32 v181, v181, v177
	s_and_saveexec_b64 s[8:9], s[0:1]
	ds_write_b32 v174, v181 offset:2304
	s_or_b64 exec, exec, s[8:9]
	s_waitcnt vmcnt(7)
	v_pk_fma_f32 v[30:31], v[30:31], 0.5, v[198:199] op_sel_hi:[1,0,1]
	v_pk_fma_f32 v[28:29], v[28:29], 0.5, v[196:197] op_sel_hi:[1,0,1]
	v_mul_f32_e32 v181, v29, v29
	v_mul_f32_e32 v180, v31, v31
	v_fmac_f32_e32 v181, v28, v28
	v_fmac_f32_e32 v180, v30, v30
	v_add_f32_e32 v181, v181, v180
	s_waitcnt vmcnt(6)
	v_pk_fma_f32 v[26:27], v[26:27], 0.5, v[202:203] op_sel_hi:[1,0,1]
	v_pk_fma_f32 v[24:25], v[24:25], 0.5, v[200:201] op_sel_hi:[1,0,1]
	v_mul_f32_e32 v177, v25, v25
	v_mul_f32_e32 v180, v27, v27
	v_fmac_f32_e32 v177, v24, v24
	v_fmac_f32_e32 v180, v26, v26
	v_add_f32_e32 v177, v177, v180
	v_add_f32_e32 v181, v181, v177
	s_waitcnt vmcnt(5)
	v_pk_fma_f32 v[22:23], v[22:23], 0.5, v[206:207] op_sel_hi:[1,0,1]
	v_pk_fma_f32 v[20:21], v[20:21], 0.5, v[204:205] op_sel_hi:[1,0,1]
	v_mul_f32_e32 v177, v21, v21
	v_mul_f32_e32 v180, v23, v23
	v_fmac_f32_e32 v177, v20, v20
	v_fmac_f32_e32 v180, v22, v22
	v_add_f32_e32 v177, v177, v180
	v_add_f32_e32 v181, v181, v177
	s_waitcnt vmcnt(4)
	v_pk_fma_f32 v[18:19], v[18:19], 0.5, v[210:211] op_sel_hi:[1,0,1]
	v_pk_fma_f32 v[16:17], v[16:17], 0.5, v[208:209] op_sel_hi:[1,0,1]
	v_mul_f32_e32 v177, v17, v17
	v_mul_f32_e32 v180, v19, v19
	v_fmac_f32_e32 v177, v16, v16
	v_fmac_f32_e32 v180, v18, v18
	v_add_f32_e32 v177, v177, v180
	v_add_f32_e32 v181, v181, v177
	ds_bpermute_b32 v177, v175, v181
	s_waitcnt lgkmcnt(0)
	v_add_f32_e32 v181, v181, v177
	ds_bpermute_b32 v177, v176, v181
	s_waitcnt lgkmcnt(0)
	v_add_f32_e32 v181, v181, v177
	s_and_saveexec_b64 s[8:9], s[0:1]
	ds_write_b32 v174, v181 offset:2560
	s_or_b64 exec, exec, s[8:9]
	s_waitcnt vmcnt(3)
	v_pk_fma_f32 v[14:15], v[14:15], 0.5, v[214:215] op_sel_hi:[1,0,1]
	v_pk_fma_f32 v[12:13], v[12:13], 0.5, v[212:213] op_sel_hi:[1,0,1]
	v_mul_f32_e32 v181, v13, v13
	v_mul_f32_e32 v180, v15, v15
	v_fmac_f32_e32 v181, v12, v12
	v_fmac_f32_e32 v180, v14, v14
	v_add_f32_e32 v181, v181, v180
	s_waitcnt vmcnt(2)
	v_pk_fma_f32 v[142:143], v[10:11], 0.5, v[218:219] op_sel_hi:[1,0,1]
	v_pk_fma_f32 v[144:145], v[8:9], 0.5, v[216:217] op_sel_hi:[1,0,1]
	v_mul_f32_e32 v177, v145, v145
	v_mul_f32_e32 v180, v143, v143
	v_fmac_f32_e32 v177, v144, v144
	v_fmac_f32_e32 v180, v142, v142
	v_add_f32_e32 v177, v177, v180
	v_add_f32_e32 v181, v181, v177
	s_waitcnt vmcnt(1)
	v_pk_fma_f32 v[8:9], v[6:7], 0.5, v[222:223] op_sel_hi:[1,0,1]
	v_pk_fma_f32 v[10:11], v[4:5], 0.5, v[220:221] op_sel_hi:[1,0,1]
	v_mul_f32_e32 v177, v11, v11
	v_mul_f32_e32 v180, v9, v9
	v_fmac_f32_e32 v177, v10, v10
	v_fmac_f32_e32 v180, v8, v8
	v_add_f32_e32 v177, v177, v180
	v_add_f32_e32 v181, v181, v177
	s_waitcnt vmcnt(0)
	v_pk_fma_f32 v[4:5], v[2:3], 0.5, v[226:227] op_sel_hi:[1,0,1]
	v_pk_fma_f32 v[6:7], v[0:1], 0.5, v[224:225] op_sel_hi:[1,0,1]
	v_mul_f32_e32 v177, v7, v7
	v_mul_f32_e32 v180, v5, v5
	v_fmac_f32_e32 v177, v6, v6
	v_fmac_f32_e32 v180, v4, v4
	v_add_f32_e32 v177, v177, v180
	v_add_f32_e32 v181, v181, v177
	ds_bpermute_b32 v177, v175, v181
	s_waitcnt lgkmcnt(0)
	v_add_f32_e32 v181, v181, v177
	ds_bpermute_b32 v177, v176, v181
	s_waitcnt lgkmcnt(0)
	v_add_f32_e32 v181, v181, v177
	s_and_saveexec_b64 s[8:9], s[0:1]
	ds_write_b32 v174, v181 offset:2816
	s_or_b64 exec, exec, s[8:9]
	global_load_dwordx4 v[196:199], v[134:135], off
	global_load_dwordx4 v[200:203], v[134:135], off offset:64
	global_load_dwordx4 v[204:207], v[134:135], off offset:512
	global_load_dwordx4 v[208:211], v[134:135], off offset:576
	v_add_u32_e32 v0, s42, v149
	s_waitcnt lgkmcnt(0)
	s_barrier
	s_waitcnt lgkmcnt(0)
	v_ashrrev_i32_e32 v1, 31, v0
	v_lshlrev_b64 v[0:1], 5, v[0:1]
	v_lshl_add_u64 v[0:1], s[24:25], 0, v[0:1]
	s_and_saveexec_b64 s[8:9], s[2:3]
	s_cbranch_execz .LBB0_670
	ds_read_b128 v[176:179], v170
	s_waitcnt lgkmcnt(0)
	v_mov_b32_e32 v2, v177
	v_mov_b32_e32 v3, v178
	v_mov_b32_e32 v177, v179
	v_pk_add_f32 v[2:3], v[2:3], v[176:177]
	v_lshl_add_u64 v[176:177], v[0:1], 0, s[12:13]
	v_pk_add_f32 v[2:3], v[2:3], v[2:3] op_sel:[0,1] op_sel_hi:[1,0]
	global_store_dword v[176:177], v2, off sc1
